# S5 carry scan: LDS reads prefetched 8 steps ahead, 4 scalar f32 FMAs per step, cvt_pk_bf16 for the carry rounding
# baseline (speedup 1.0000x reference)
; #define LAS __attribute__((address_space(3)))
; #define LDS_WAIT() asm volatile("s_waitcnt lgkmcnt(0)" ::: "memory")
; __device__ __forceinline__ int fresh_tid(const Frame& F) { unsigned m_ = ~0u; asm volatile("" : "+s"(m_)); return F.wave * 64 + (int)__builtin_amdgcn_mbcnt_hi(m_, __builtin_amdgcn_mbcnt_lo(m_, 0u)); }
;     __device__ __forceinline__ void fused(const Acc& acc, const Unit&, int wr, int wc, int fr, int fq, LAS unsigned char* lds) const {
;     ...
;         LAS float* S = (LAS float*)lds;
; #pragma unroll
;         for (int ai = 0; ai < 2; ++ai)
; #pragma unroll
;             for (int m = 0; m < 4; ++m)
; #pragma unroll
;                 for (int n = 0; n < 2; ++n) *(LAS f32x4*)(S + (ai * 128 + wr * 64 + m * 16 + fr) * SLD + wc * 32 + n * 16 + 4 * fq) = acc[ai][0][m][n];
; __device__ __forceinline__ void p2_ssm(const Frame& F, ArgsP a, int l) {
;     ...
;         LDS_WAIT(); __syncthreads();
;         int t2 = fresh_tid(F); asm volatile("" : "+v"(t2));
;         if (t2 < 128) {
;             const int bb = t2 >> 6, n = t2 & 63; const float2 a16 = ((const float2*)(F.ws + WS_A16))[lg * 64 + n];
;             LAS float* S = (LAS float*)F.lds + (bb * 128) * SLD;
;             float sr = 0.f, si = 0.f;
.LBB0_505:
	s_lshl_b32 s3, s5, 6
	s_barrier
	s_movk_i32 s14, 0x210
	v_add_u32_e32 v0, s3, v67
	s_lshl_b32 s3, s4, 7
	s_add_i32 s3, s3, 0
	v_lshlrev_b32_e32 v66, 4, v66
	v_mul_lo_u32 v0, v0, s14
	v_add3_u32 v0, s3, v66, v0
	ds_write_b128 v0, v[2:5]
	ds_write_b128 v0, v[6:9] offset:64
	ds_write_b128 v0, v[10:13] offset:8448
	ds_write_b128 v0, v[14:17] offset:8512
	ds_write_b128 v0, v[18:21] offset:16896
	ds_write_b128 v0, v[22:25] offset:16960
	ds_write_b128 v0, v[26:29] offset:25344
	ds_write_b128 v0, v[30:33] offset:25408
	v_add_u32_e32 v2, 0x10800, v0
	ds_write_b128 v2, v[34:37]
	v_add_u32_e32 v2, 0x10840, v0
	ds_write_b128 v2, v[38:41]
	v_add_u32_e32 v2, 0x12900, v0
	ds_write_b128 v2, v[42:45]
	v_add_u32_e32 v2, 0x12940, v0
	ds_write_b128 v2, v[46:49]
	v_add_u32_e32 v2, 0x14a00, v0
	ds_write_b128 v2, v[50:53]
	v_add_u32_e32 v2, 0x14a40, v0
	ds_write_b128 v2, v[54:57]
	v_add_u32_e32 v2, 0x16b00, v0
	v_add_u32_e32 v0, 0x16b40, v0
	ds_write_b128 v2, v[58:61]
	ds_write_b128 v0, v[62:65]
	s_mov_b32 s3, -1
	s_waitcnt lgkmcnt(0)
	s_waitcnt vmcnt(0) lgkmcnt(0)
	s_barrier
	s_nop 0
	v_mbcnt_lo_u32_b32 v0, s3, 0
	v_mbcnt_hi_u32_b32 v0, s3, v0
	v_add_u32_e32 v8, s95, v0
	s_nop 0
	v_cmp_gt_i32_e32 vcc, s11, v8
	s_and_saveexec_b64 s[38:39], vcc
	s_cbranch_execz .LBB0_508
	v_and_b32_e32 v0, 63, v8
	v_lshl_or_b32 v2, s2, 6, v0
	v_readlane_b32 s4, v255, 48
	v_ashrrev_i32_e32 v3, 31, v2
	v_readlane_b32 s5, v255, 49
	v_lshlrev_b32_e32 v4, 1, v8
	v_and_b32_e32 v4, 0xfffff80, v4
	v_lshl_add_u64 v[2:3], v[2:3], 3, s[4:5]
	global_load_dwordx2 v[2:3], v[2:3], off
	v_mov_b32_e32 v6, 0
	v_lshlrev_b32_e32 v0, 2, v0
	v_mul_lo_u32 v4, v4, s14
	s_mov_b32 s3, 0
	v_add3_u32 v0, 0, v4, v0
	v_mov_b32_e32 v7, v6
	ds_read_b32 v16, v0 offset:0
	ds_read_b32 v17, v0 offset:256
	ds_read_b32 v18, v0 offset:528
	ds_read_b32 v19, v0 offset:784
	ds_read_b32 v20, v0 offset:1056
	ds_read_b32 v21, v0 offset:1312
	ds_read_b32 v22, v0 offset:1584
	ds_read_b32 v23, v0 offset:1840
	ds_read_b32 v24, v0 offset:2112
	ds_read_b32 v25, v0 offset:2368
	ds_read_b32 v26, v0 offset:2640
	ds_read_b32 v27, v0 offset:2896
	ds_read_b32 v28, v0 offset:3168
	ds_read_b32 v29, v0 offset:3424
	ds_read_b32 v30, v0 offset:3696
	ds_read_b32 v31, v0 offset:3952
	s_waitcnt vmcnt(0)
	v_xor_b32_e32 v4, 0x80000000, v3
; __device__ __forceinline__ unsigned f2bf(float f) { unsigned u = __builtin_bit_cast(unsigned, f); return (u + 0x7fffu + ((u >> 16) & 1u)) >> 16; }
; __device__ __forceinline__ void p2_ssm(const Frame& F, ArgsP a, int l) {
;     ...
;             float sr = 0.f, si = 0.f;
; #pragma unroll 8
;             for (int c = 0; c < 128; ++c) { const float lr = S[c * SLD + n], li = S[c * SLD + 64 + n];
;                 S[c * SLD + n] = __builtin_bit_cast(float, f2bf(sr)); S[c * SLD + 64 + n] = __builtin_bit_cast(float, f2bf(si));
;                 const float nr = a16.x * sr - a16.y * si + lr, ni = a16.x * si + a16.y * sr + li; sr = nr; si = ni; }
.LBB0_507:
	v_add_u32_e32 v9, s3, v0
	ds_read_b32 v32, v9 offset:4224
	ds_read_b32 v33, v9 offset:4480
	s_waitcnt lgkmcnt(12)
	v_fma_f32 v12, v2, v6, v16
	v_fma_f32 v13, v2, v7, v17
	v_cvt_pk_bf16_f32 v14, v6, v7
	v_fma_f32 v10, v4, v7, v12
	v_fma_f32 v11, v3, v6, v13
	v_lshrrev_b32_e32 v15, 16, v14
	ds_write_b32 v9, v14 offset:0
	ds_write_b32 v9, v15 offset:256
	ds_read_b32 v34, v9 offset:4752
	ds_read_b32 v35, v9 offset:5008
	s_waitcnt lgkmcnt(12)
	v_fma_f32 v12, v2, v10, v18
	v_fma_f32 v13, v2, v11, v19
	v_cvt_pk_bf16_f32 v14, v10, v11
	v_fma_f32 v6, v4, v11, v12
	v_fma_f32 v7, v3, v10, v13
	v_lshrrev_b32_e32 v15, 16, v14
	ds_write_b32 v9, v14 offset:528
	ds_write_b32 v9, v15 offset:784
	ds_read_b32 v36, v9 offset:5280
	ds_read_b32 v37, v9 offset:5536
	s_waitcnt lgkmcnt(12)
	v_fma_f32 v12, v2, v6, v20
	v_fma_f32 v13, v2, v7, v21
	v_cvt_pk_bf16_f32 v14, v6, v7
	v_fma_f32 v10, v4, v7, v12
	v_fma_f32 v11, v3, v6, v13
	v_lshrrev_b32_e32 v15, 16, v14
	ds_write_b32 v9, v14 offset:1056
	ds_write_b32 v9, v15 offset:1312
	ds_read_b32 v38, v9 offset:5808
	ds_read_b32 v39, v9 offset:6064
	s_waitcnt lgkmcnt(12)
	v_fma_f32 v12, v2, v10, v22
	v_fma_f32 v13, v2, v11, v23
	v_cvt_pk_bf16_f32 v14, v10, v11
	v_fma_f32 v6, v4, v11, v12
	v_fma_f32 v7, v3, v10, v13
	v_lshrrev_b32_e32 v15, 16, v14
	ds_write_b32 v9, v14 offset:1584
	ds_write_b32 v9, v15 offset:1840
	ds_read_b32 v40, v9 offset:6336
	ds_read_b32 v41, v9 offset:6592
	s_waitcnt lgkmcnt(12)
	v_fma_f32 v12, v2, v6, v24
	v_fma_f32 v13, v2, v7, v25
	v_cvt_pk_bf16_f32 v14, v6, v7
	v_fma_f32 v10, v4, v7, v12
	v_fma_f32 v11, v3, v6, v13
	v_lshrrev_b32_e32 v15, 16, v14
	ds_write_b32 v9, v14 offset:2112
	ds_write_b32 v9, v15 offset:2368
	ds_read_b32 v42, v9 offset:6864
	ds_read_b32 v43, v9 offset:7120
	s_waitcnt lgkmcnt(12)
	v_fma_f32 v12, v2, v10, v26
	v_fma_f32 v13, v2, v11, v27
	v_cvt_pk_bf16_f32 v14, v10, v11
	v_fma_f32 v6, v4, v11, v12
	v_fma_f32 v7, v3, v10, v13
	v_lshrrev_b32_e32 v15, 16, v14
	ds_write_b32 v9, v14 offset:2640
	ds_write_b32 v9, v15 offset:2896
	ds_read_b32 v44, v9 offset:7392
	ds_read_b32 v45, v9 offset:7648
	s_waitcnt lgkmcnt(12)
	v_fma_f32 v12, v2, v6, v28
	v_fma_f32 v13, v2, v7, v29
	v_cvt_pk_bf16_f32 v14, v6, v7
	v_fma_f32 v10, v4, v7, v12
	v_fma_f32 v11, v3, v6, v13
	v_lshrrev_b32_e32 v15, 16, v14
	ds_write_b32 v9, v14 offset:3168
	ds_write_b32 v9, v15 offset:3424
	ds_read_b32 v46, v9 offset:7920
	ds_read_b32 v47, v9 offset:8176
	s_waitcnt lgkmcnt(12)
	v_fma_f32 v12, v2, v10, v30
	v_fma_f32 v13, v2, v11, v31
	v_cvt_pk_bf16_f32 v14, v10, v11
	v_fma_f32 v6, v4, v11, v12
	v_fma_f32 v7, v3, v10, v13
	v_lshrrev_b32_e32 v15, 16, v14
	ds_write_b32 v9, v14 offset:3696
	ds_write_b32 v9, v15 offset:3952
	ds_read_b32 v16, v9 offset:8448
	ds_read_b32 v17, v9 offset:8704
	s_waitcnt lgkmcnt(12)
	v_fma_f32 v12, v2, v6, v32
	v_fma_f32 v13, v2, v7, v33
	v_cvt_pk_bf16_f32 v14, v6, v7
	v_fma_f32 v10, v4, v7, v12
	v_fma_f32 v11, v3, v6, v13
	v_lshrrev_b32_e32 v15, 16, v14
	ds_write_b32 v9, v14 offset:4224
	ds_write_b32 v9, v15 offset:4480
	ds_read_b32 v18, v9 offset:8976
	ds_read_b32 v19, v9 offset:9232
	s_waitcnt lgkmcnt(12)
	v_fma_f32 v12, v2, v10, v34
	v_fma_f32 v13, v2, v11, v35
	v_cvt_pk_bf16_f32 v14, v10, v11
	v_fma_f32 v6, v4, v11, v12
	v_fma_f32 v7, v3, v10, v13
	v_lshrrev_b32_e32 v15, 16, v14
	ds_write_b32 v9, v14 offset:4752
	ds_write_b32 v9, v15 offset:5008
	ds_read_b32 v20, v9 offset:9504
	ds_read_b32 v21, v9 offset:9760
	s_waitcnt lgkmcnt(12)
	v_fma_f32 v12, v2, v6, v36
	v_fma_f32 v13, v2, v7, v37
	v_cvt_pk_bf16_f32 v14, v6, v7
	v_fma_f32 v10, v4, v7, v12
	v_fma_f32 v11, v3, v6, v13
	v_lshrrev_b32_e32 v15, 16, v14
	ds_write_b32 v9, v14 offset:5280
	ds_write_b32 v9, v15 offset:5536
	ds_read_b32 v22, v9 offset:10032
	ds_read_b32 v23, v9 offset:10288
	s_waitcnt lgkmcnt(12)
	v_fma_f32 v12, v2, v10, v38
	v_fma_f32 v13, v2, v11, v39
	v_cvt_pk_bf16_f32 v14, v10, v11
	v_fma_f32 v6, v4, v11, v12
	v_fma_f32 v7, v3, v10, v13
	v_lshrrev_b32_e32 v15, 16, v14
	ds_write_b32 v9, v14 offset:5808
	ds_write_b32 v9, v15 offset:6064
	ds_read_b32 v24, v9 offset:10560
	ds_read_b32 v25, v9 offset:10816
	s_waitcnt lgkmcnt(12)
	v_fma_f32 v12, v2, v6, v40
	v_fma_f32 v13, v2, v7, v41
	v_cvt_pk_bf16_f32 v14, v6, v7
	v_fma_f32 v10, v4, v7, v12
	v_fma_f32 v11, v3, v6, v13
	v_lshrrev_b32_e32 v15, 16, v14
	ds_write_b32 v9, v14 offset:6336
	ds_write_b32 v9, v15 offset:6592
	ds_read_b32 v26, v9 offset:11088
	ds_read_b32 v27, v9 offset:11344
	s_waitcnt lgkmcnt(12)
	v_fma_f32 v12, v2, v10, v42
	v_fma_f32 v13, v2, v11, v43
	v_cvt_pk_bf16_f32 v14, v10, v11
	v_fma_f32 v6, v4, v11, v12
	v_fma_f32 v7, v3, v10, v13
	v_lshrrev_b32_e32 v15, 16, v14
	ds_write_b32 v9, v14 offset:6864
	ds_write_b32 v9, v15 offset:7120
	ds_read_b32 v28, v9 offset:11616
	ds_read_b32 v29, v9 offset:11872
	s_waitcnt lgkmcnt(12)
	v_fma_f32 v12, v2, v6, v44
	v_fma_f32 v13, v2, v7, v45
	v_cvt_pk_bf16_f32 v14, v6, v7
	v_fma_f32 v10, v4, v7, v12
	v_fma_f32 v11, v3, v6, v13
	v_lshrrev_b32_e32 v15, 16, v14
	ds_write_b32 v9, v14 offset:7392
	ds_write_b32 v9, v15 offset:7648
	ds_read_b32 v30, v9 offset:12144
	ds_read_b32 v31, v9 offset:12400
	s_waitcnt lgkmcnt(12)
	v_fma_f32 v12, v2, v10, v46
	v_fma_f32 v13, v2, v11, v47
	v_cvt_pk_bf16_f32 v14, v10, v11
	v_fma_f32 v6, v4, v11, v12
	v_fma_f32 v7, v3, v10, v13
	v_lshrrev_b32_e32 v15, 16, v14
	ds_write_b32 v9, v14 offset:7920
	ds_write_b32 v9, v15 offset:8176
	s_addk_i32 s3, 0x2100
	s_cmp_lg_u32 s3, 0x10800
	s_cbranch_scc1 .LBB0_507
